# index key-tile loop: redundant canonicalising v_max dropped (bit-identical)
# speedup vs baseline: 1.0188x; 1.0090x over previous
; __device__ __forceinline__ unsigned ordkey(float f) { const unsigned u = __float_as_uint(f); return u ^ ((u >> 31) ? 0xFFFFFFFFu : 0x80000000u); }
; __device__ __forceinline__ void dsa_index_unit(const Ctx& c, int l, int b, int qb) {
;     ...
;             f32x16 acc;
; #pragma unroll
;             for (int v = 0; v < 16; ++v) acc[v] = 0.f;
; #pragma unroll
;             for (int ks = 0; ks < 4; ++ks) acc = __builtin_amdgcn_mfma_f32_32x32x16_bf16(Af[ks], Bc[ks], acc, 0, 0, 0);
;             float sc = 0.f;
; #pragma unroll
;             for (int v = 0; v < 16; ++v) sc += wq[v] * fmaxf(acc[v], 0.f);
;             if (kt == qb && n > (tq & 31)) sc = -INFINITY;
;             sk[kt * 64 + lane] = ordkey(sc);
.Lit0_nodma0:
	s_cmp_eq_u32 s16, s44
	s_cselect_b64 s[0:1], -1, 0
	s_and_b64 s[0:1], s[0:1], vcc
	s_waitcnt lgkmcnt(0)
	v_mfma_f32_32x32x16_bf16 v[0:15], v[18:21], v[46:49], 0
	v_mfma_f32_32x32x16_bf16 v[0:15], v[22:25], v[50:53], v[0:15]
	v_mfma_f32_32x32x16_bf16 v[0:15], v[26:29], v[54:57], v[0:15]
	v_mfma_f32_32x32x16_bf16 v[0:15], v[30:33], v[58:61], v[0:15]
	s_nop 7
	s_nop 4
	v_max_f32_e32 v0, 0, v0
	v_fma_f32 v16, v88, v0, 0
	v_max_f32_e32 v0, 0, v1
	v_fmac_f32_e32 v16, v89, v0
	v_max_f32_e32 v0, 0, v2
	v_fmac_f32_e32 v16, v90, v0
	v_max_f32_e32 v0, 0, v3
	v_fmac_f32_e32 v16, v91, v0
	v_max_f32_e32 v0, 0, v4
	v_fmac_f32_e32 v16, v92, v0
	v_max_f32_e32 v0, 0, v5
	v_fmac_f32_e32 v16, v93, v0
	v_max_f32_e32 v0, 0, v6
	v_max_f32_e32 v1, 0, v7
	v_pk_mul_f32 v[0:1], v[76:77], v[0:1]
	s_nop 0
	v_add_f32_e32 v0, v0, v16
	v_add_f32_e32 v2, v1, v0
	v_max_f32_e32 v0, 0, v8
	v_max_f32_e32 v1, 0, v9
	v_pk_mul_f32 v[0:1], v[78:79], v[0:1]
	s_nop 0
	v_add_f32_e32 v0, v0, v2
	v_add_f32_e32 v2, v1, v0
	v_max_f32_e32 v0, 0, v10
	v_max_f32_e32 v1, 0, v11
	v_pk_mul_f32 v[0:1], v[80:81], v[0:1]
	s_nop 0
	v_add_f32_e32 v0, v0, v2
	v_add_f32_e32 v2, v1, v0
	v_max_f32_e32 v0, 0, v12
	v_max_f32_e32 v1, 0, v13
	v_pk_mul_f32 v[0:1], v[82:83], v[0:1]
	s_nop 0
	v_add_f32_e32 v0, v0, v2
	v_add_f32_e32 v2, v1, v0
	v_max_f32_e32 v0, 0, v14
	v_max_f32_e32 v1, 0, v15
	v_pk_mul_f32 v[0:1], v[84:85], v[0:1]
	s_nop 0
	v_add_f32_e32 v0, v0, v2
	v_add_f32_e32 v0, v1, v0
	v_cndmask_b32_e64 v0, v0, v139, s[0:1]
	v_cmp_lt_i32_e64 s[0:1], -1, v0
	s_nop 1
	v_cndmask_b32_e64 v1, -1, v140, s[0:1]
	v_xor_b32_e32 v0, v1, v0
	ds_write_b32 v94, v0
	v_add_u32_e32 v94, 0x100, v94
	s_add_i32 s44, s44, 1
	s_cmp_eq_u32 s18, s44
	s_cbranch_scc1 .Lit0_done

; __device__ __forceinline__ unsigned ordkey(float f) { const unsigned u = __float_as_uint(f); return u ^ ((u >> 31) ? 0xFFFFFFFFu : 0x80000000u); }
; __device__ __forceinline__ void dsa_index_unit(const Ctx& c, int l, int b, int qb) {
;     ...
;             f32x16 acc;
; #pragma unroll
;             for (int v = 0; v < 16; ++v) acc[v] = 0.f;
; #pragma unroll
;             for (int ks = 0; ks < 4; ++ks) acc = __builtin_amdgcn_mfma_f32_32x32x16_bf16(Af[ks], Bc[ks], acc, 0, 0, 0);
;             float sc = 0.f;
; #pragma unroll
;             for (int v = 0; v < 16; ++v) sc += wq[v] * fmaxf(acc[v], 0.f);
;             if (kt == qb && n > (tq & 31)) sc = -INFINITY;
;             sk[kt * 64 + lane] = ordkey(sc);
.Lit0_nodma3:
	s_cmp_eq_u32 s16, s44
	s_cselect_b64 s[0:1], -1, 0
	s_and_b64 s[0:1], s[0:1], vcc
	s_waitcnt lgkmcnt(0)
	v_mfma_f32_32x32x16_bf16 v[0:15], v[18:21], v[46:49], 0
	v_mfma_f32_32x32x16_bf16 v[0:15], v[22:25], v[50:53], v[0:15]
	v_mfma_f32_32x32x16_bf16 v[0:15], v[26:29], v[54:57], v[0:15]
	v_mfma_f32_32x32x16_bf16 v[0:15], v[30:33], v[58:61], v[0:15]
	s_nop 7
	s_nop 4
	v_max_f32_e32 v0, 0, v0
	v_fma_f32 v16, v88, v0, 0
	v_max_f32_e32 v0, 0, v1
	v_fmac_f32_e32 v16, v89, v0
	v_max_f32_e32 v0, 0, v2
	v_fmac_f32_e32 v16, v90, v0
	v_max_f32_e32 v0, 0, v3
	v_fmac_f32_e32 v16, v91, v0
	v_max_f32_e32 v0, 0, v4
	v_fmac_f32_e32 v16, v92, v0
	v_max_f32_e32 v0, 0, v5
	v_fmac_f32_e32 v16, v93, v0
	v_max_f32_e32 v0, 0, v6
	v_max_f32_e32 v1, 0, v7
	v_pk_mul_f32 v[0:1], v[76:77], v[0:1]
	s_nop 0
	v_add_f32_e32 v0, v0, v16
	v_add_f32_e32 v2, v1, v0
	v_max_f32_e32 v0, 0, v8
	v_max_f32_e32 v1, 0, v9
	v_pk_mul_f32 v[0:1], v[78:79], v[0:1]
	s_nop 0
	v_add_f32_e32 v0, v0, v2
	v_add_f32_e32 v2, v1, v0
	v_max_f32_e32 v0, 0, v10
	v_max_f32_e32 v1, 0, v11
	v_pk_mul_f32 v[0:1], v[80:81], v[0:1]
	s_nop 0
	v_add_f32_e32 v0, v0, v2
	v_add_f32_e32 v2, v1, v0
	v_max_f32_e32 v0, 0, v12
	v_max_f32_e32 v1, 0, v13
	v_pk_mul_f32 v[0:1], v[82:83], v[0:1]
	s_nop 0
	v_add_f32_e32 v0, v0, v2
	v_add_f32_e32 v2, v1, v0
	v_max_f32_e32 v0, 0, v14
	v_max_f32_e32 v1, 0, v15
	v_pk_mul_f32 v[0:1], v[84:85], v[0:1]
	s_nop 0
	v_add_f32_e32 v0, v0, v2
	v_add_f32_e32 v0, v1, v0
	v_cndmask_b32_e64 v0, v0, v139, s[0:1]
	v_cmp_lt_i32_e64 s[0:1], -1, v0
	s_nop 1
	v_cndmask_b32_e64 v1, -1, v140, s[0:1]
	v_xor_b32_e32 v0, v1, v0
	ds_write_b32 v94, v0
	v_add_u32_e32 v94, 0x100, v94
	s_add_i32 s44, s44, 1
	s_cmp_eq_u32 s18, s44
	s_cbranch_scc1 .Lit0_done
	s_branch .Lit0_step0

; __device__ __forceinline__ unsigned ordkey(float f) { const unsigned u = __float_as_uint(f); return u ^ ((u >> 31) ? 0xFFFFFFFFu : 0x80000000u); }
; __device__ __forceinline__ void dsa_index_unit(const Ctx& c, int l, int b, int qb) {
;     ...
;             f32x16 acc;
; #pragma unroll
;             for (int v = 0; v < 16; ++v) acc[v] = 0.f;
; #pragma unroll
;             for (int ks = 0; ks < 4; ++ks) acc = __builtin_amdgcn_mfma_f32_32x32x16_bf16(Af[ks], Bc[ks], acc, 0, 0, 0);
;             float sc = 0.f;
; #pragma unroll
;             for (int v = 0; v < 16; ++v) sc += wq[v] * fmaxf(acc[v], 0.f);
;             if (kt == qb && n > (tq & 31)) sc = -INFINITY;
;             sk[kt * 64 + lane] = ordkey(sc);
.Lit1_nodma0:
	s_cmp_eq_u32 s14, s44
	s_cselect_b64 s[0:1], -1, 0
	s_and_b64 s[0:1], s[0:1], vcc
	s_waitcnt lgkmcnt(0)
	v_mfma_f32_32x32x16_bf16 v[0:15], v[18:21], v[46:49], 0
	v_mfma_f32_32x32x16_bf16 v[0:15], v[22:25], v[50:53], v[0:15]
	v_mfma_f32_32x32x16_bf16 v[0:15], v[26:29], v[54:57], v[0:15]
	v_mfma_f32_32x32x16_bf16 v[0:15], v[30:33], v[58:61], v[0:15]
	s_nop 7
	s_nop 4
	v_max_f32_e32 v0, 0, v0
	v_fma_f32 v16, v88, v0, 0
	v_max_f32_e32 v0, 0, v1
	v_fmac_f32_e32 v16, v89, v0
	v_max_f32_e32 v0, 0, v2
	v_fmac_f32_e32 v16, v90, v0
	v_max_f32_e32 v0, 0, v3
	v_fmac_f32_e32 v16, v91, v0
	v_max_f32_e32 v0, 0, v4
	v_fmac_f32_e32 v16, v92, v0
	v_max_f32_e32 v0, 0, v5
	v_fmac_f32_e32 v16, v93, v0
	v_max_f32_e32 v0, 0, v6
	v_max_f32_e32 v1, 0, v7
	v_pk_mul_f32 v[0:1], v[76:77], v[0:1]
	s_nop 0
	v_add_f32_e32 v0, v0, v16
	v_add_f32_e32 v2, v1, v0
	v_max_f32_e32 v0, 0, v8
	v_max_f32_e32 v1, 0, v9
	v_pk_mul_f32 v[0:1], v[78:79], v[0:1]
	s_nop 0
	v_add_f32_e32 v0, v0, v2
	v_add_f32_e32 v2, v1, v0
	v_max_f32_e32 v0, 0, v10
	v_max_f32_e32 v1, 0, v11
	v_pk_mul_f32 v[0:1], v[80:81], v[0:1]
	s_nop 0
	v_add_f32_e32 v0, v0, v2
	v_add_f32_e32 v2, v1, v0
	v_max_f32_e32 v0, 0, v12
	v_max_f32_e32 v1, 0, v13
	v_pk_mul_f32 v[0:1], v[82:83], v[0:1]
	s_nop 0
	v_add_f32_e32 v0, v0, v2
	v_add_f32_e32 v2, v1, v0
	v_max_f32_e32 v0, 0, v14
	v_max_f32_e32 v1, 0, v15
	v_pk_mul_f32 v[0:1], v[84:85], v[0:1]
	s_nop 0
	v_add_f32_e32 v0, v0, v2
	v_add_f32_e32 v0, v1, v0
	v_cndmask_b32_e64 v0, v0, v139, s[0:1]
	v_cmp_lt_i32_e64 s[0:1], -1, v0
	s_nop 1
	v_cndmask_b32_e64 v1, -1, v140, s[0:1]
	v_xor_b32_e32 v0, v1, v0
	ds_write_b32 v94, v0
	v_add_u32_e32 v94, 0x100, v94
	s_add_i32 s44, s44, 1
	s_cmp_eq_u32 s18, s44
	s_cbranch_scc1 .Lit1_done

; __device__ __forceinline__ unsigned ordkey(float f) { const unsigned u = __float_as_uint(f); return u ^ ((u >> 31) ? 0xFFFFFFFFu : 0x80000000u); }
; __device__ __forceinline__ void dsa_index_unit(const Ctx& c, int l, int b, int qb) {
;     ...
;             f32x16 acc;
; #pragma unroll
;             for (int v = 0; v < 16; ++v) acc[v] = 0.f;
; #pragma unroll
;             for (int ks = 0; ks < 4; ++ks) acc = __builtin_amdgcn_mfma_f32_32x32x16_bf16(Af[ks], Bc[ks], acc, 0, 0, 0);
;             float sc = 0.f;
; #pragma unroll
;             for (int v = 0; v < 16; ++v) sc += wq[v] * fmaxf(acc[v], 0.f);
;             if (kt == qb && n > (tq & 31)) sc = -INFINITY;
;             sk[kt * 64 + lane] = ordkey(sc);
.Lit1_nodma3:
	s_cmp_eq_u32 s14, s44
	s_cselect_b64 s[0:1], -1, 0
	s_and_b64 s[0:1], s[0:1], vcc
	s_waitcnt lgkmcnt(0)
	v_mfma_f32_32x32x16_bf16 v[0:15], v[18:21], v[46:49], 0
	v_mfma_f32_32x32x16_bf16 v[0:15], v[22:25], v[50:53], v[0:15]
	v_mfma_f32_32x32x16_bf16 v[0:15], v[26:29], v[54:57], v[0:15]
	v_mfma_f32_32x32x16_bf16 v[0:15], v[30:33], v[58:61], v[0:15]
	s_nop 7
	s_nop 4
	v_max_f32_e32 v0, 0, v0
	v_fma_f32 v16, v88, v0, 0
	v_max_f32_e32 v0, 0, v1
	v_fmac_f32_e32 v16, v89, v0
	v_max_f32_e32 v0, 0, v2
	v_fmac_f32_e32 v16, v90, v0
	v_max_f32_e32 v0, 0, v3
	v_fmac_f32_e32 v16, v91, v0
	v_max_f32_e32 v0, 0, v4
	v_fmac_f32_e32 v16, v92, v0
	v_max_f32_e32 v0, 0, v5
	v_fmac_f32_e32 v16, v93, v0
	v_max_f32_e32 v0, 0, v6
	v_max_f32_e32 v1, 0, v7
	v_pk_mul_f32 v[0:1], v[76:77], v[0:1]
	s_nop 0
	v_add_f32_e32 v0, v0, v16
	v_add_f32_e32 v2, v1, v0
	v_max_f32_e32 v0, 0, v8
	v_max_f32_e32 v1, 0, v9
	v_pk_mul_f32 v[0:1], v[78:79], v[0:1]
	s_nop 0
	v_add_f32_e32 v0, v0, v2
	v_add_f32_e32 v2, v1, v0
	v_max_f32_e32 v0, 0, v10
	v_max_f32_e32 v1, 0, v11
	v_pk_mul_f32 v[0:1], v[80:81], v[0:1]
	s_nop 0
	v_add_f32_e32 v0, v0, v2
	v_add_f32_e32 v2, v1, v0
	v_max_f32_e32 v0, 0, v12
	v_max_f32_e32 v1, 0, v13
	v_pk_mul_f32 v[0:1], v[82:83], v[0:1]
	s_nop 0
	v_add_f32_e32 v0, v0, v2
	v_add_f32_e32 v2, v1, v0
	v_max_f32_e32 v0, 0, v14
	v_max_f32_e32 v1, 0, v15
	v_pk_mul_f32 v[0:1], v[84:85], v[0:1]
	s_nop 0
	v_add_f32_e32 v0, v0, v2
	v_add_f32_e32 v0, v1, v0
	v_cndmask_b32_e64 v0, v0, v139, s[0:1]
	v_cmp_lt_i32_e64 s[0:1], -1, v0
	s_nop 1
	v_cndmask_b32_e64 v1, -1, v140, s[0:1]
	v_xor_b32_e32 v0, v1, v0
	ds_write_b32 v94, v0
	v_add_u32_e32 v94, 0x100, v94
	s_add_i32 s44, s44, 1
	s_cmp_eq_u32 s18, s44
	s_cbranch_scc1 .Lit1_done
	s_branch .Lit1_step0
